# attention softmax: scale multiply of the next element moved into the v_cmp-to-v_cndmask hazard slot (replaces s_nop), on top of the sink-load hoist
# speedup vs baseline: 1.0004x; 1.0004x over previous
; __device__ __forceinline__ unsigned pack2(float a, float b) { unsigned r; asm("v_cvt_pk_bf16_f32 %0, %1, %2" : "=v"(r) : "v"(a), "v"(b)); return r; }
; __device__ __forceinline__ void attn_item(const Params& p, int layer, bool isctx, int item, unsigned char* smem) {
;     ...
;     __syncthreads();
; #pragma unroll
;     for (int i = 0; i < 2; i++) {
;       int e = tid + NT * i;
;       int r = e >> 3, cch = (e & 7) * 8;
;       *(uint4*)(Ks + r * 72 + cch) = *(const uint4*)(KR + (size_t)(krow0 + r) * 128 + kvh * 64 + cch);
;       int d = e >> 4, kc = (e & 15) * 8;
;       *(uint4*)(Vt + d * 136 + kc) = *(const uint4*)(VT + (size_t)(kvh * 64 + d) * TA + krow0 + kc);
;     }
;     __syncthreads();
; #pragma unroll
;     for (int k4 = 0; k4 < 4; k4++) {
;       f32x16 st;
; #pragma unroll
;       for (int r = 0; r < 16; r++) st[r] = 0.f;
; #pragma unroll
;       for (int ks = 0; ks < 4; ks++) {
;         bf16x8 kf = *(const bf16x8*)(Ks + (k4 * 32 + (lane & 31)) * 72 + ks * 16 + hh * 8);
;         st = __builtin_amdgcn_mfma_f32_32x32x16_bf16(kf, qf[ks], st, 0, 0, 0);
;       }
;       float pe[16];
; #pragma unroll
;       for (int r = 0; r < 16; r++) {
;         int kl = k4 * 32 + (r & 3) + 8 * (r >> 2) + 4 * hh;
;         float e = __expf(st[r] * 0.125f);
;         bool valid = (mtype * kl) <= mq;
;         e = valid ? e : 0.f;
;         pe[r] = e; rsum += e;
;       }
;       bf16x8 pb[2];
; #pragma unroll
;       for (int s = 0; s < 2; s++) {
;         union { bf16x8 v; unsigned w[4]; } cv;
; #pragma unroll
;         for (int q = 0; q < 4; q++) cv.w[q] = pack2(pe[8 * s + 2 * q], pe[8 * s + 2 * q + 1]);
;         pb[s] = cv.v;
;       }
; #pragma unroll
;       for (int mt = 0; mt < 2; mt++)
; #pragma unroll
;         for (int s = 0; s < 2; s++) {
;           const u16* vp = Vt + (mt * 32 + (lane & 31)) * 136 + k4 * 32 + 16 * s + 4 * hh;
;           union { bf16x8 v; uint2 h2[2]; } av;
;           av.h2[0] = *(const uint2*)vp;
;           av.h2[1] = *(const uint2*)(vp + 8);
;           oacc[mt] = __builtin_amdgcn_mfma_f32_32x32x16_bf16(av.v, pb[s], oacc[mt], 0, 0, 0);
;         }
.LBB0_488:
	v_add_u32_e32 v32, s8, v82
	v_ashrrev_i32_e32 v33, 31, v32
	v_lshlrev_b64 v[32:33], 8, v[32:33]
	v_lshl_add_u64 v[32:33], v[68:69], 0, v[32:33]
	s_waitcnt lgkmcnt(0)
	s_barrier
	global_load_dwordx4 v[40:43], v[32:33], off
	s_ashr_i32 s9, s8, 31
	v_lshl_add_u64 v[36:37], s[8:9], 1, v[70:71]
	v_mul_lo_u32 v88, s19, v81
	v_mul_lo_u32 v87, s19, v67
	v_cmp_le_i32_e32 vcc, v87, v88
	v_lshl_add_u64 v[32:33], v[36:37], 0, v[74:75]
	global_load_dwordx4 v[44:47], v[32:33], off
	v_add_u32_e32 v32, s8, v83
	v_ashrrev_i32_e32 v33, 31, v32
	v_lshlrev_b64 v[32:33], 8, v[32:33]
	v_lshl_add_u64 v[32:33], v[68:69], 0, v[32:33]
	global_load_dwordx4 v[90:93], v[32:33], off
	v_lshl_add_u64 v[32:33], v[36:37], 0, v[78:79]
	global_load_dwordx4 v[32:35], v[32:33], off
	s_mul_i32 s8, s19, 5
	s_waitcnt vmcnt(3)
	ds_write_b128 v72, v[40:43]
	s_waitcnt vmcnt(2)
	ds_write_b128 v73, v[44:47]
	s_waitcnt vmcnt(1)
	ds_write_b128 v76, v[90:93]
	s_waitcnt vmcnt(0)
	ds_write_b128 v77, v[32:35]
	s_waitcnt lgkmcnt(0)
	s_barrier
	ds_read_b128 v[32:35], v84
	ds_read_b128 v[90:93], v84 offset:32
	s_waitcnt lgkmcnt(1)
	v_mfma_f32_32x32x16_bf16 v[32:47], v[32:35], v[56:59], 0
	s_waitcnt lgkmcnt(0)
	v_mfma_f32_32x32x16_bf16 v[32:47], v[90:93], v[48:51], v[32:47]
	ds_read_b128 v[90:93], v84 offset:64
	s_waitcnt lgkmcnt(0)
	v_mfma_f32_32x32x16_bf16 v[32:47], v[90:93], v[52:55], v[32:47]
	ds_read_b128 v[90:93], v84 offset:96
	s_waitcnt lgkmcnt(0)
	v_mfma_f32_32x32x16_bf16 v[32:47], v[90:93], v[60:63], v[32:47]
	s_nop 11
	v_mul_f32_e32 v32, 0x3e38aa3b, v32
	v_exp_f32_e32 v32, v32
	v_mul_f32_e32 v99, 0x3e38aa3b, v33
	v_cndmask_b32_e32 v89, 0, v32, vcc
	v_exp_f32_e32 v32, v99
	v_add_u32_e32 v33, s19, v87
	v_cmp_le_i32_e32 vcc, v33, v88
	v_add_u32_e32 v33, s19, v33
	v_mul_f32_e32 v99, 0x3e38aa3b, v34
	v_cndmask_b32_e32 v87, 0, v32, vcc
	v_exp_f32_e32 v32, v99
	v_cmp_le_i32_e32 vcc, v33, v88
	v_add_u32_e32 v33, s19, v33
	v_mul_f32_e32 v99, 0x3e38aa3b, v35
	v_cndmask_b32_e32 v90, 0, v32, vcc
	v_exp_f32_e32 v32, v99
	v_cmp_le_i32_e32 vcc, v33, v88
	v_add_u32_e32 v33, s8, v33
	v_mul_f32_e32 v99, 0x3e38aa3b, v36
	v_cndmask_b32_e32 v91, 0, v32, vcc
	v_exp_f32_e32 v32, v99
	v_cmp_le_i32_e32 vcc, v33, v88
	v_add_u32_e32 v33, s19, v33
	v_mul_f32_e32 v99, 0x3e38aa3b, v37
	v_cndmask_b32_e32 v92, 0, v32, vcc
	v_exp_f32_e32 v32, v99
	v_cmp_le_i32_e32 vcc, v33, v88
	v_add_u32_e32 v33, s19, v33
	v_mul_f32_e32 v99, 0x3e38aa3b, v38
	v_cndmask_b32_e32 v93, 0, v32, vcc
	v_exp_f32_e32 v32, v99
	v_cmp_le_i32_e32 vcc, v33, v88
	v_add_u32_e32 v33, s19, v33
	v_cvt_pk_bf16_f32 v34, v92, v93
	v_mul_f32_e32 v99, 0x3e38aa3b, v39
	v_cndmask_b32_e32 v94, 0, v32, vcc
	v_exp_f32_e32 v32, v99
	v_cmp_le_i32_e32 vcc, v33, v88
	v_add_u32_e32 v33, s8, v33
	v_mul_f32_e32 v99, 0x3e38aa3b, v40
	v_cndmask_b32_e32 v95, 0, v32, vcc
	v_exp_f32_e32 v32, v99
	v_cmp_le_i32_e32 vcc, v33, v88
	v_add_u32_e32 v33, s19, v33
	v_cvt_pk_bf16_f32 v35, v94, v95
	v_mul_f32_e32 v99, 0x3e38aa3b, v41
	v_cndmask_b32_e32 v40, 0, v32, vcc
	v_exp_f32_e32 v32, v99
	v_cmp_le_i32_e32 vcc, v33, v88
	v_add_u32_e32 v33, s19, v33
	v_mul_f32_e32 v99, 0x3e38aa3b, v42
	v_cndmask_b32_e32 v41, 0, v32, vcc
	v_exp_f32_e32 v32, v99
	v_cmp_le_i32_e32 vcc, v33, v88
	v_add_u32_e32 v33, s19, v33
	v_cvt_pk_bf16_f32 v36, v40, v41
	v_mul_f32_e32 v99, 0x3e38aa3b, v43
	v_cndmask_b32_e32 v42, 0, v32, vcc
	v_exp_f32_e32 v32, v99
	v_cmp_le_i32_e32 vcc, v33, v88
	v_add_u32_e32 v33, s8, v33
	v_mul_f32_e32 v99, 0x3e38aa3b, v44
	v_cndmask_b32_e32 v43, 0, v32, vcc
	v_exp_f32_e32 v32, v99
	v_cmp_le_i32_e32 vcc, v33, v88
	v_add_u32_e32 v33, s19, v33
	v_cvt_pk_bf16_f32 v37, v42, v43
	v_mul_f32_e32 v99, 0x3e38aa3b, v45
	v_cndmask_b32_e32 v44, 0, v32, vcc
	v_exp_f32_e32 v32, v99
	v_cmp_le_i32_e32 vcc, v33, v88
	v_add_u32_e32 v33, s19, v33
	v_add_u32_e32 v96, s19, v33
	v_cndmask_b32_e32 v45, 0, v32, vcc
	v_mul_f32_e32 v32, 0x3e38aa3b, v46
	v_exp_f32_e32 v32, v32
	v_cmp_le_i32_e32 vcc, v33, v88
	v_cvt_pk_bf16_f32 v38, v44, v45
	v_cvt_pk_bf16_f32 v33, v90, v91
	s_nop 1
	v_cndmask_b32_e32 v46, 0, v32, vcc
	v_mul_f32_e32 v32, 0x3e38aa3b, v47
	v_add_f32_e32 v47, v86, v89
	v_add_f32_e32 v47, v87, v47
	v_add_f32_e32 v47, v90, v47
	v_add_f32_e32 v47, v91, v47
	v_add_f32_e32 v47, v92, v47
	v_add_f32_e32 v47, v93, v47
	v_add_f32_e32 v47, v94, v47
	v_add_f32_e32 v47, v95, v47
	v_add_f32_e32 v40, v40, v47
	v_exp_f32_e32 v32, v32
	v_add_f32_e32 v40, v41, v40
	v_add_f32_e32 v40, v42, v40
	v_add_f32_e32 v40, v43, v40
	v_cmp_le_i32_e32 vcc, v96, v88
	v_add_f32_e32 v40, v44, v40
	v_add_f32_e32 v40, v45, v40
	v_cndmask_b32_e32 v97, 0, v32, vcc
	v_cvt_pk_bf16_f32 v32, v89, v87
	v_add_u32_e32 v87, 0x4800, v85
	v_cvt_pk_bf16_f32 v39, v46, v97
	v_add_f32_e32 v89, v46, v40
	ds_read2_b64 v[40:43], v87 offset1:2
	ds_read2_b64 v[44:47], v87 offset0:4 offset1:6
	v_add_u32_e32 v86, 0x6800, v85
	s_waitcnt lgkmcnt(1)
	v_mfma_f32_32x32x16_bf16 v[16:31], v[40:43], v[32:35], v[16:31]
	ds_read2_b64 v[40:43], v86 offset0:64 offset1:66
	ds_read_b128 v[92:95], v84 offset:4640
	v_add_f32_e32 v90, v97, v89
	v_add_u32_e32 v89, s8, v96
	v_cmp_le_i32_e32 vcc, v89, v88
	s_waitcnt lgkmcnt(1)
	v_mfma_f32_32x32x16_bf16 v[0:15], v[40:43], v[32:35], v[0:15]
	ds_read2_b64 v[32:35], v86 offset0:68 offset1:70
	s_waitcnt lgkmcnt(0)
	v_mfma_f32_32x32x16_bf16 v[0:15], v[32:35], v[36:39], v[0:15]
	ds_read_b128 v[32:35], v84 offset:4608
	v_mfma_f32_32x32x16_bf16 v[16:31], v[44:47], v[36:39], v[16:31]
	s_waitcnt lgkmcnt(0)
	v_mfma_f32_32x32x16_bf16 v[32:47], v[32:35], v[56:59], 0
	v_mfma_f32_32x32x16_bf16 v[32:47], v[92:95], v[48:51], v[32:47]
	ds_read_b128 v[92:95], v84 offset:4672
	s_waitcnt lgkmcnt(0)
; __device__ __forceinline__ unsigned pack2(float a, float b) { unsigned r; asm("v_cvt_pk_bf16_f32 %0, %1, %2" : "=v"(r) : "v"(a), "v"(b)); return r; }
; __device__ __forceinline__ void attn_item(const Params& p, int layer, bool isctx, int item, unsigned char* smem) {
;     ...
;     for (int k4 = 0; k4 < 4; k4++) {
;       f32x16 st;
; #pragma unroll
;       for (int r = 0; r < 16; r++) st[r] = 0.f;
; #pragma unroll
;       for (int ks = 0; ks < 4; ks++) {
;         bf16x8 kf = *(const bf16x8*)(Ks + (k4 * 32 + (lane & 31)) * 72 + ks * 16 + hh * 8);
;         st = __builtin_amdgcn_mfma_f32_32x32x16_bf16(kf, qf[ks], st, 0, 0, 0);
;       }
;       float pe[16];
; #pragma unroll
;       for (int r = 0; r < 16; r++) {
;         int kl = k4 * 32 + (r & 3) + 8 * (r >> 2) + 4 * hh;
;         float e = __expf(st[r] * 0.125f);
;         bool valid = (mtype * kl) <= mq;
;         e = valid ? e : 0.f;
;         pe[r] = e; rsum += e;
;       }
;       bf16x8 pb[2];
; #pragma unroll
;       for (int s = 0; s < 2; s++) {
;         union { bf16x8 v; unsigned w[4]; } cv;
; #pragma unroll
;         for (int q = 0; q < 4; q++) cv.w[q] = pack2(pe[8 * s + 2 * q], pe[8 * s + 2 * q + 1]);
;         pb[s] = cv.v;
;       }
; #pragma unroll
;       for (int mt = 0; mt < 2; mt++)
; #pragma unroll
;         for (int s = 0; s < 2; s++) {
;           const u16* vp = Vt + (mt * 32 + (lane & 31)) * 136 + k4 * 32 + 16 * s + 4 * hh;
;           union { bf16x8 v; uint2 h2[2]; } av;
;           av.h2[0] = *(const uint2*)vp;
;           av.h2[1] = *(const uint2*)(vp + 8);
;           oacc[mt] = __builtin_amdgcn_mfma_f32_32x32x16_bf16(av.v, pb[s], oacc[mt], 0, 0, 0);
;         }
;     }
	v_mfma_f32_32x32x16_bf16 v[32:47], v[92:95], v[52:55], v[32:47]
	ds_read_b128 v[92:95], v84 offset:4704
	s_waitcnt lgkmcnt(0)
	v_mfma_f32_32x32x16_bf16 v[32:47], v[92:95], v[60:63], v[32:47]
	s_nop 11
	v_mul_f32_e32 v32, 0x3e38aa3b, v32
	v_exp_f32_e32 v32, v32
	v_mul_f32_e32 v99, 0x3e38aa3b, v33
	v_cndmask_b32_e32 v91, 0, v32, vcc
	v_exp_f32_e32 v32, v99
	v_add_u32_e32 v33, s19, v89
	v_cmp_le_i32_e32 vcc, v33, v88
	v_add_u32_e32 v33, s19, v33
	v_add_f32_e32 v90, v90, v91
	v_cndmask_b32_e32 v92, 0, v32, vcc
	v_mul_f32_e32 v32, 0x3e38aa3b, v34
	v_exp_f32_e32 v32, v32
	v_cmp_le_i32_e32 vcc, v33, v88
	v_add_u32_e32 v33, s19, v33
	v_add_f32_e32 v90, v92, v90
	v_cndmask_b32_e32 v93, 0, v32, vcc
	v_mul_f32_e32 v32, 0x3e38aa3b, v35
	v_exp_f32_e32 v32, v32
	v_cmp_le_i32_e32 vcc, v33, v88
	v_add_u32_e32 v33, s8, v33
	v_add_f32_e32 v90, v93, v90
	v_cndmask_b32_e32 v94, 0, v32, vcc
	v_mul_f32_e32 v32, 0x3e38aa3b, v36
	v_exp_f32_e32 v32, v32
	v_cmp_le_i32_e32 vcc, v33, v88
	v_add_u32_e32 v33, s19, v33
	v_add_f32_e32 v90, v94, v90
	v_cndmask_b32_e32 v95, 0, v32, vcc
	v_mul_f32_e32 v32, 0x3e38aa3b, v37
	v_exp_f32_e32 v32, v32
	v_cmp_le_i32_e32 vcc, v33, v88
	v_add_u32_e32 v33, s19, v33
	v_add_f32_e32 v90, v95, v90
	v_cndmask_b32_e32 v96, 0, v32, vcc
	v_mul_f32_e32 v32, 0x3e38aa3b, v38
	v_exp_f32_e32 v32, v32
	v_cmp_le_i32_e32 vcc, v33, v88
	v_add_u32_e32 v33, s19, v33
	v_add_f32_e32 v90, v96, v90
	v_cndmask_b32_e32 v97, 0, v32, vcc
	v_mul_f32_e32 v32, 0x3e38aa3b, v39
	v_exp_f32_e32 v32, v32
	v_cmp_le_i32_e32 vcc, v33, v88
	v_add_u32_e32 v33, s8, v33
	v_add_f32_e32 v90, v97, v90
	v_cndmask_b32_e32 v98, 0, v32, vcc
	v_mul_f32_e32 v32, 0x3e38aa3b, v40
	v_exp_f32_e32 v32, v32
	v_cmp_le_i32_e32 vcc, v33, v88
	v_add_u32_e32 v33, s19, v33
	v_add_f32_e32 v90, v98, v90
	v_cndmask_b32_e32 v40, 0, v32, vcc
	v_mul_f32_e32 v32, 0x3e38aa3b, v41
	v_exp_f32_e32 v32, v32
	v_cmp_le_i32_e32 vcc, v33, v88
	v_add_u32_e32 v33, s19, v33
	v_cvt_pk_bf16_f32 v34, v95, v96
	v_cvt_pk_bf16_f32 v35, v97, v98
	v_mul_f32_e32 v99, 0x3e38aa3b, v42
	v_cndmask_b32_e32 v41, 0, v32, vcc
	v_exp_f32_e32 v32, v99
	v_cmp_le_i32_e32 vcc, v33, v88
	v_add_u32_e32 v33, s19, v33
	v_cvt_pk_bf16_f32 v36, v40, v41
	v_add_f32_e32 v40, v40, v90
	v_cndmask_b32_e32 v42, 0, v32, vcc
	v_mul_f32_e32 v32, 0x3e38aa3b, v43
	v_exp_f32_e32 v32, v32
	v_cmp_le_i32_e32 vcc, v33, v88
	v_add_u32_e32 v33, s8, v33
	v_add_f32_e32 v40, v41, v40
	v_cndmask_b32_e32 v43, 0, v32, vcc
	v_mul_f32_e32 v32, 0x3e38aa3b, v44
	v_exp_f32_e32 v32, v32
	v_cmp_le_i32_e32 vcc, v33, v88
	v_add_u32_e32 v33, s19, v33
	v_add_f32_e32 v40, v42, v40
	v_cndmask_b32_e32 v44, 0, v32, vcc
	v_mul_f32_e32 v32, 0x3e38aa3b, v45
	v_exp_f32_e32 v32, v32
	v_cmp_le_i32_e32 vcc, v33, v88
	v_add_u32_e32 v33, s19, v33
	v_add_f32_e32 v40, v43, v40
	v_cndmask_b32_e32 v45, 0, v32, vcc
	v_mul_f32_e32 v32, 0x3e38aa3b, v46
	v_exp_f32_e32 v32, v32
	v_cmp_le_i32_e32 vcc, v33, v88
	v_add_f32_e32 v40, v44, v40
	v_add_f32_e32 v40, v45, v40
	v_cndmask_b32_e32 v46, 0, v32, vcc
	v_cvt_pk_bf16_f32 v37, v42, v43
	v_cvt_pk_bf16_f32 v38, v44, v45
	v_add_f32_e32 v44, v46, v40
	ds_read2_b64 v[40:43], v87 offset0:8 offset1:10
	v_mul_f32_e32 v32, 0x3e38aa3b, v47
	v_exp_f32_e32 v32, v32
	v_add_u32_e32 v89, s19, v33
	v_cmp_le_i32_e32 vcc, v89, v88
	v_cvt_pk_bf16_f32 v33, v93, v94
	v_add_u32_e32 v89, s8, v89
	s_nop 0
	v_cndmask_b32_e32 v47, 0, v32, vcc
	v_cvt_pk_bf16_f32 v32, v91, v92
	v_cvt_pk_bf16_f32 v39, v46, v47
	ds_read_b128 v[92:95], v84 offset:9248
	s_waitcnt lgkmcnt(1)
	v_mfma_f32_32x32x16_bf16 v[16:31], v[40:43], v[32:35], v[16:31]
	ds_read2_b64 v[40:43], v87 offset0:12 offset1:14
	v_add_f32_e32 v90, v47, v44
	v_cmp_le_i32_e32 vcc, v89, v88
	s_waitcnt lgkmcnt(0)
	v_mfma_f32_32x32x16_bf16 v[16:31], v[40:43], v[36:39], v[16:31]
	ds_read2_b64 v[40:43], v86 offset0:72 offset1:74
	s_waitcnt lgkmcnt(0)
	v_mfma_f32_32x32x16_bf16 v[0:15], v[40:43], v[32:35], v[0:15]
	ds_read2_b64 v[32:35], v86 offset0:76 offset1:78
	s_waitcnt lgkmcnt(0)
	v_mfma_f32_32x32x16_bf16 v[0:15], v[32:35], v[36:39], v[0:15]
	ds_read_b128 v[32:35], v84 offset:9216
	s_waitcnt lgkmcnt(0)
	v_mfma_f32_32x32x16_bf16 v[32:47], v[32:35], v[56:59], 0
	v_mfma_f32_32x32x16_bf16 v[32:47], v[92:95], v[48:51], v[32:47]
	ds_read_b128 v[92:95], v84 offset:9280
	s_waitcnt lgkmcnt(0)
	v_mfma_f32_32x32x16_bf16 v[32:47], v[92:95], v[52:55], v[32:47]
	ds_read_b128 v[92:95], v84 offset:9312
	s_waitcnt lgkmcnt(0)
; __device__ __forceinline__ unsigned pack2(float a, float b) { unsigned r; asm("v_cvt_pk_bf16_f32 %0, %1, %2" : "=v"(r) : "v"(a), "v"(b)); return r; }
; __device__ __forceinline__ void attn_item(const Params& p, int layer, bool isctx, int item, unsigned char* smem) {
;     ...
;     for (int k4 = 0; k4 < 4; k4++) {
;       f32x16 st;
; #pragma unroll
;       for (int r = 0; r < 16; r++) st[r] = 0.f;
; #pragma unroll
;       for (int ks = 0; ks < 4; ks++) {
;         bf16x8 kf = *(const bf16x8*)(Ks + (k4 * 32 + (lane & 31)) * 72 + ks * 16 + hh * 8);
;         st = __builtin_amdgcn_mfma_f32_32x32x16_bf16(kf, qf[ks], st, 0, 0, 0);
;       }
;       float pe[16];
; #pragma unroll
;       for (int r = 0; r < 16; r++) {
;         int kl = k4 * 32 + (r & 3) + 8 * (r >> 2) + 4 * hh;
;         float e = __expf(st[r] * 0.125f);
;         bool valid = (mtype * kl) <= mq;
;         e = valid ? e : 0.f;
;         pe[r] = e; rsum += e;
;       }
;       bf16x8 pb[2];
; #pragma unroll
;       for (int s = 0; s < 2; s++) {
;         union { bf16x8 v; unsigned w[4]; } cv;
; #pragma unroll
;         for (int q = 0; q < 4; q++) cv.w[q] = pack2(pe[8 * s + 2 * q], pe[8 * s + 2 * q + 1]);
;         pb[s] = cv.v;
;       }
; #pragma unroll
;       for (int mt = 0; mt < 2; mt++)
; #pragma unroll
;         for (int s = 0; s < 2; s++) {
;           const u16* vp = Vt + (mt * 32 + (lane & 31)) * 136 + k4 * 32 + 16 * s + 4 * hh;
;           union { bf16x8 v; uint2 h2[2]; } av;
;           av.h2[0] = *(const uint2*)vp;
;           av.h2[1] = *(const uint2*)(vp + 8);
;           oacc[mt] = __builtin_amdgcn_mfma_f32_32x32x16_bf16(av.v, pb[s], oacc[mt], 0, 0, 0);
;         }
;     }
	v_mfma_f32_32x32x16_bf16 v[32:47], v[92:95], v[60:63], v[32:47]
	s_nop 11
	v_mul_f32_e32 v32, 0x3e38aa3b, v32
	v_exp_f32_e32 v32, v32
	v_mul_f32_e32 v99, 0x3e38aa3b, v33
	v_cndmask_b32_e32 v91, 0, v32, vcc
	v_exp_f32_e32 v32, v99
	v_add_u32_e32 v33, s19, v89
	v_cmp_le_i32_e32 vcc, v33, v88
	v_add_u32_e32 v33, s19, v33
	v_add_f32_e32 v90, v90, v91
	v_cndmask_b32_e32 v92, 0, v32, vcc
	v_mul_f32_e32 v32, 0x3e38aa3b, v34
	v_exp_f32_e32 v32, v32
	v_cmp_le_i32_e32 vcc, v33, v88
	v_add_u32_e32 v33, s19, v33
	v_add_f32_e32 v90, v92, v90
	v_cndmask_b32_e32 v93, 0, v32, vcc
	v_mul_f32_e32 v32, 0x3e38aa3b, v35
	v_exp_f32_e32 v32, v32
	v_cmp_le_i32_e32 vcc, v33, v88
	v_add_u32_e32 v33, s8, v33
	v_add_f32_e32 v90, v93, v90
	v_cndmask_b32_e32 v94, 0, v32, vcc
	v_mul_f32_e32 v32, 0x3e38aa3b, v36
	v_exp_f32_e32 v32, v32
	v_cmp_le_i32_e32 vcc, v33, v88
	v_add_u32_e32 v33, s19, v33
	v_add_f32_e32 v90, v94, v90
	v_cndmask_b32_e32 v95, 0, v32, vcc
	v_mul_f32_e32 v32, 0x3e38aa3b, v37
	v_exp_f32_e32 v32, v32
	v_cmp_le_i32_e32 vcc, v33, v88
	v_add_u32_e32 v33, s19, v33
	v_add_f32_e32 v90, v95, v90
	v_cndmask_b32_e32 v96, 0, v32, vcc
	v_mul_f32_e32 v32, 0x3e38aa3b, v38
	v_exp_f32_e32 v32, v32
	v_cmp_le_i32_e32 vcc, v33, v88
	v_add_u32_e32 v33, s19, v33
	v_add_f32_e32 v90, v96, v90
	v_cndmask_b32_e32 v97, 0, v32, vcc
	v_mul_f32_e32 v32, 0x3e38aa3b, v39
	v_exp_f32_e32 v32, v32
	v_cmp_le_i32_e32 vcc, v33, v88
	v_add_u32_e32 v33, s8, v33
	v_add_f32_e32 v90, v97, v90
	v_cndmask_b32_e32 v98, 0, v32, vcc
	v_mul_f32_e32 v32, 0x3e38aa3b, v40
	v_exp_f32_e32 v32, v32
	v_cmp_le_i32_e32 vcc, v33, v88
	v_add_u32_e32 v33, s19, v33
	v_add_f32_e32 v90, v98, v90
	v_cndmask_b32_e32 v40, 0, v32, vcc
	v_mul_f32_e32 v32, 0x3e38aa3b, v41
	v_exp_f32_e32 v32, v32
	v_cmp_le_i32_e32 vcc, v33, v88
	v_add_u32_e32 v33, s19, v33
	v_cvt_pk_bf16_f32 v34, v95, v96
	v_cvt_pk_bf16_f32 v35, v97, v98
	v_mul_f32_e32 v99, 0x3e38aa3b, v42
	v_cndmask_b32_e32 v41, 0, v32, vcc
	v_exp_f32_e32 v32, v99
	v_cmp_le_i32_e32 vcc, v33, v88
	v_add_u32_e32 v33, s19, v33
	v_cvt_pk_bf16_f32 v36, v40, v41
	v_add_f32_e32 v40, v40, v90
	v_cndmask_b32_e32 v42, 0, v32, vcc
	v_mul_f32_e32 v32, 0x3e38aa3b, v43
	v_exp_f32_e32 v32, v32
	v_cmp_le_i32_e32 vcc, v33, v88
	v_add_u32_e32 v33, s8, v33
	v_add_f32_e32 v40, v41, v40
	v_cndmask_b32_e32 v43, 0, v32, vcc
	v_mul_f32_e32 v32, 0x3e38aa3b, v44
	v_exp_f32_e32 v32, v32
	v_cmp_le_i32_e32 vcc, v33, v88
	v_add_u32_e32 v33, s19, v33
	v_add_f32_e32 v40, v42, v40
	v_cndmask_b32_e32 v44, 0, v32, vcc
	v_mul_f32_e32 v32, 0x3e38aa3b, v45
	v_exp_f32_e32 v32, v32
	v_cmp_le_i32_e32 vcc, v33, v88
	v_add_u32_e32 v33, s19, v33
	v_add_f32_e32 v40, v43, v40
	v_cndmask_b32_e32 v45, 0, v32, vcc
	v_mul_f32_e32 v32, 0x3e38aa3b, v46
	v_exp_f32_e32 v32, v32
	v_cmp_le_i32_e32 vcc, v33, v88
	v_add_f32_e32 v40, v44, v40
	v_add_f32_e32 v40, v45, v40
	v_cndmask_b32_e32 v46, 0, v32, vcc
	v_cvt_pk_bf16_f32 v37, v42, v43
	v_cvt_pk_bf16_f32 v38, v44, v45
	v_add_f32_e32 v44, v46, v40
	ds_read2_b64 v[40:43], v87 offset0:16 offset1:18
	v_mul_f32_e32 v32, 0x3e38aa3b, v47
	v_exp_f32_e32 v32, v32
	v_add_u32_e32 v89, s19, v33
	v_cmp_le_i32_e32 vcc, v89, v88
	v_cvt_pk_bf16_f32 v33, v93, v94
	v_add_u32_e32 v89, s8, v89
	s_nop 0
	v_cndmask_b32_e32 v47, 0, v32, vcc
	v_cvt_pk_bf16_f32 v32, v91, v92
	v_cvt_pk_bf16_f32 v39, v46, v47
	ds_read_b128 v[92:95], v84 offset:13856
	s_waitcnt lgkmcnt(1)
	v_mfma_f32_32x32x16_bf16 v[16:31], v[40:43], v[32:35], v[16:31]
	ds_read2_b64 v[40:43], v87 offset0:20 offset1:22
	v_add_f32_e32 v90, v47, v44
	v_cmp_le_i32_e32 vcc, v89, v88
	s_waitcnt lgkmcnt(0)
	v_mfma_f32_32x32x16_bf16 v[16:31], v[40:43], v[36:39], v[16:31]
	ds_read2_b64 v[40:43], v86 offset0:80 offset1:82
	s_waitcnt lgkmcnt(0)
	v_mfma_f32_32x32x16_bf16 v[0:15], v[40:43], v[32:35], v[0:15]
	ds_read2_b64 v[32:35], v86 offset0:84 offset1:86
	s_waitcnt lgkmcnt(0)
	v_mfma_f32_32x32x16_bf16 v[0:15], v[32:35], v[36:39], v[0:15]
	ds_read_b128 v[32:35], v84 offset:13824
	s_waitcnt lgkmcnt(0)
	v_mfma_f32_32x32x16_bf16 v[32:47], v[32:35], v[56:59], 0
	v_mfma_f32_32x32x16_bf16 v[32:47], v[92:95], v[48:51], v[32:47]
	ds_read_b128 v[92:95], v84 offset:13888
	s_waitcnt lgkmcnt(0)
; __device__ __forceinline__ unsigned pack2(float a, float b) { unsigned r; asm("v_cvt_pk_bf16_f32 %0, %1, %2" : "=v"(r) : "v"(a), "v"(b)); return r; }
; __device__ __forceinline__ void attn_item(const Params& p, int layer, bool isctx, int item, unsigned char* smem) {
;     ...
;     for (int k4 = 0; k4 < 4; k4++) {
;       f32x16 st;
; #pragma unroll
;       for (int r = 0; r < 16; r++) st[r] = 0.f;
; #pragma unroll
;       for (int ks = 0; ks < 4; ks++) {
;         bf16x8 kf = *(const bf16x8*)(Ks + (k4 * 32 + (lane & 31)) * 72 + ks * 16 + hh * 8);
;         st = __builtin_amdgcn_mfma_f32_32x32x16_bf16(kf, qf[ks], st, 0, 0, 0);
;       }
;       float pe[16];
; #pragma unroll
;       for (int r = 0; r < 16; r++) {
;         int kl = k4 * 32 + (r & 3) + 8 * (r >> 2) + 4 * hh;
;         float e = __expf(st[r] * 0.125f);
;         bool valid = (mtype * kl) <= mq;
;         e = valid ? e : 0.f;
;         pe[r] = e; rsum += e;
;       }
;       bf16x8 pb[2];
; #pragma unroll
;       for (int s = 0; s < 2; s++) {
;         union { bf16x8 v; unsigned w[4]; } cv;
; #pragma unroll
;         for (int q = 0; q < 4; q++) cv.w[q] = pack2(pe[8 * s + 2 * q], pe[8 * s + 2 * q + 1]);
;         pb[s] = cv.v;
;       }
; #pragma unroll
;       for (int mt = 0; mt < 2; mt++)
; #pragma unroll
;         for (int s = 0; s < 2; s++) {
;           const u16* vp = Vt + (mt * 32 + (lane & 31)) * 136 + k4 * 32 + 16 * s + 4 * hh;
;           union { bf16x8 v; uint2 h2[2]; } av;
;           av.h2[0] = *(const uint2*)vp;
;           av.h2[1] = *(const uint2*)(vp + 8);
;           oacc[mt] = __builtin_amdgcn_mfma_f32_32x32x16_bf16(av.v, pb[s], oacc[mt], 0, 0, 0);
;         }
;     }
	v_mfma_f32_32x32x16_bf16 v[32:47], v[92:95], v[52:55], v[32:47]
	ds_read_b128 v[92:95], v84 offset:13920
	s_waitcnt lgkmcnt(0)
	v_mfma_f32_32x32x16_bf16 v[32:47], v[92:95], v[60:63], v[32:47]
	s_nop 11
	v_mul_f32_e32 v32, 0x3e38aa3b, v32
	v_exp_f32_e32 v32, v32
	v_mul_f32_e32 v99, 0x3e38aa3b, v33
	v_cndmask_b32_e32 v91, 0, v32, vcc
	v_exp_f32_e32 v32, v99
	v_add_u32_e32 v33, s19, v89
	v_cmp_le_i32_e32 vcc, v33, v88
	v_add_u32_e32 v33, s19, v33
	v_mul_f32_e32 v99, 0x3e38aa3b, v34
	v_cndmask_b32_e32 v89, 0, v32, vcc
	v_exp_f32_e32 v32, v99
	v_cmp_le_i32_e32 vcc, v33, v88
	v_add_u32_e32 v33, s19, v33
	v_mul_f32_e32 v99, 0x3e38aa3b, v35
	v_cndmask_b32_e32 v92, 0, v32, vcc
	v_exp_f32_e32 v32, v99
	v_cmp_le_i32_e32 vcc, v33, v88
	v_add_u32_e32 v33, s8, v33
	v_mul_f32_e32 v99, 0x3e38aa3b, v36
	v_cndmask_b32_e32 v93, 0, v32, vcc
	v_exp_f32_e32 v32, v99
	v_cmp_le_i32_e32 vcc, v33, v88
	v_add_u32_e32 v33, s19, v33
	v_cvt_pk_bf16_f32 v36, v91, v89
	v_mul_f32_e32 v99, 0x3e38aa3b, v37
	v_cndmask_b32_e32 v94, 0, v32, vcc
	v_exp_f32_e32 v32, v99
	v_cmp_le_i32_e32 vcc, v33, v88
	v_add_u32_e32 v33, s19, v33
	v_cvt_pk_bf16_f32 v37, v92, v93
	v_mul_f32_e32 v99, 0x3e38aa3b, v38
	v_cndmask_b32_e32 v95, 0, v32, vcc
	v_exp_f32_e32 v32, v99
	v_cmp_le_i32_e32 vcc, v33, v88
	v_add_u32_e32 v33, s19, v33
	v_cvt_pk_bf16_f32 v38, v94, v95
	v_mul_f32_e32 v99, 0x3e38aa3b, v39
	v_cndmask_b32_e32 v96, 0, v32, vcc
	v_exp_f32_e32 v32, v99
	v_cmp_le_i32_e32 vcc, v33, v88
	v_add_u32_e32 v33, s8, v33
	v_mul_f32_e32 v99, 0x3e38aa3b, v40
	v_cndmask_b32_e32 v97, 0, v32, vcc
	v_exp_f32_e32 v32, v99
	v_cmp_le_i32_e32 vcc, v33, v88
	v_add_u32_e32 v33, s19, v33
	v_cvt_pk_bf16_f32 v39, v96, v97
	v_mul_f32_e32 v99, 0x3e38aa3b, v41
	v_cndmask_b32_e32 v40, 0, v32, vcc
	v_exp_f32_e32 v32, v99
	v_cmp_le_i32_e32 vcc, v33, v88
	v_add_u32_e32 v33, s19, v33
	v_mul_f32_e32 v99, 0x3e38aa3b, v42
	v_cndmask_b32_e32 v41, 0, v32, vcc
	v_exp_f32_e32 v32, v99
	v_cmp_le_i32_e32 vcc, v33, v88
	v_add_u32_e32 v33, s19, v33
	v_mul_f32_e32 v99, 0x3e38aa3b, v43
	v_cndmask_b32_e32 v42, 0, v32, vcc
	v_exp_f32_e32 v32, v99
	v_cmp_le_i32_e32 vcc, v33, v88
	v_add_u32_e32 v33, s8, v33
	v_mul_f32_e32 v99, 0x3e38aa3b, v44
	v_cndmask_b32_e32 v43, 0, v32, vcc
	v_exp_f32_e32 v32, v99
	v_cmp_le_i32_e32 vcc, v33, v88
	v_add_u32_e32 v33, s19, v33
	v_mul_f32_e32 v99, 0x3e38aa3b, v45
	v_cndmask_b32_e32 v44, 0, v32, vcc
	v_exp_f32_e32 v32, v99
	v_cmp_le_i32_e32 vcc, v33, v88
	v_add_u32_e32 v33, s19, v33
	v_mul_f32_e32 v99, 0x3e38aa3b, v46
	v_cndmask_b32_e32 v45, 0, v32, vcc
	v_exp_f32_e32 v32, v99
	v_cmp_le_i32_e32 vcc, v33, v88
	v_add_u32_e32 v33, s19, v33
	v_cvt_pk_bf16_f32 v34, v44, v45
	s_nop 0
	v_cndmask_b32_e32 v46, 0, v32, vcc
	v_cmp_le_i32_e32 vcc, v33, v88
	v_add_f32_e32 v88, v90, v91
	v_add_f32_e32 v88, v89, v88
	v_mul_f32_e32 v32, 0x3e38aa3b, v47
	v_add_f32_e32 v88, v92, v88
	v_add_f32_e32 v88, v93, v88
	v_exp_f32_e32 v32, v32
	v_add_f32_e32 v88, v94, v88
	v_add_f32_e32 v88, v95, v88
	v_add_f32_e32 v88, v96, v88
	v_add_f32_e32 v88, v97, v88
	v_cndmask_b32_e32 v47, 0, v32, vcc
	v_cvt_pk_bf16_f32 v32, v40, v41
	v_add_f32_e32 v40, v40, v88
	v_add_f32_e32 v40, v41, v40
	v_add_f32_e32 v40, v42, v40
	v_add_f32_e32 v40, v43, v40
	v_add_f32_e32 v40, v44, v40
	v_add_f32_e32 v40, v45, v40
	v_cvt_pk_bf16_f32 v33, v42, v43
	v_add_f32_e32 v44, v46, v40
	ds_read2_b64 v[40:43], v87 offset0:24 offset1:26
	s_waitcnt lgkmcnt(0)
	v_mfma_f32_32x32x16_bf16 v[16:31], v[40:43], v[36:39], v[16:31]
	ds_read2_b64 v[40:43], v87 offset0:28 offset1:30
	v_cvt_pk_bf16_f32 v35, v46, v47
	s_waitcnt lgkmcnt(0)
	v_mfma_f32_32x32x16_bf16 v[16:31], v[40:43], v[32:35], v[16:31]
	ds_read2_b64 v[40:43], v86 offset0:88 offset1:90
	s_waitcnt lgkmcnt(0)
	v_mfma_f32_32x32x16_bf16 v[0:15], v[40:43], v[36:39], v[0:15]
	ds_read2_b64 v[36:39], v86 offset0:92 offset1:94
	v_add_f32_e32 v86, v47, v44
	s_waitcnt lgkmcnt(0)
	v_mfma_f32_32x32x16_bf16 v[0:15], v[36:39], v[32:35], v[0:15]
	s_add_i32 s15, s15, 1
	s_addk_i32 s17, 0x80
	s_cmp_lg_u32 s18, 4
	s_cbranch_scc0 .LBB0_482
